# GEMM K-loops (P2,P4,P6,P10): LDS-DMA via scalar running base + 32-bit lane offset (saddr form), no per-lane 64-bit address adds
# speedup vs baseline: 1.0334x; 1.0129x over previous
; #define MFMA(a, b, c) __builtin_amdgcn_mfma_f32_32x32x16_bf16((a), (b), (c), 0, 0, 0)
; #define G_BARRIER() { asm volatile("s_waitcnt vmcnt(0) lgkmcnt(0)" ::: "memory"); __builtin_amdgcn_s_barrier(); asm volatile("" ::: "memory"); }
;     ...
; #pragma unroll
;         for (int a = 0; a < 2; ++a)
; #pragma unroll
;             for (int b = 0; b < TB; ++b)
; #pragma unroll
;                 for (int i = 0; i < 16; ++i) acc[a][b][i] = 0.f;
;         G_BARRIER();
;         for (int kt = 0; kt < nk; ++kt) {
;             if (kt + 1 < nk) { G_DMA(kt + 1, (kt + 1) & 1); }
;             const unsigned char* sa = lds + (kt & 1) * 65536 + (wt * 32 * TB + r) * 128;
;             const unsigned char* sw = lds + (kt & 1) * 65536 + 32768 + (wf * 64 + r) * 128;
; #pragma unroll
;             for (int ks = 0; ks < 4; ++ks) {
;                 bf16x8 wfr[2], afr[TB];
; #pragma unroll
;                 for (int fb = 0; fb < 2; ++fb) wfr[fb] = *(const bf16x8*)(sw + fb * 4096 + koff[ks]);
; #pragma unroll
;                 for (int tb = 0; tb < TB; ++tb) afr[tb] = *(const bf16x8*)(sa + tb * 4096 + koff[ks]);
; #pragma unroll
;                 for (int fb = 0; fb < 2; ++fb)
; #pragma unroll
;                     for (int tb = 0; tb < TB; ++tb) acc[fb][tb] = MFMA(wfr[fb], afr[tb], acc[fb][tb]);
;             }
;             G_BARRIER();
.LBB0_201:
	s_waitcnt vmcnt(0) lgkmcnt(0)
	s_barrier
	v_mov_b32_e32 v0, 0
	s_mov_b32 s7, 0
	s_mov_b64 s[4:5], 0
	v_mov_b32_e32 v1, v0
	v_mov_b32_e32 v2, v0
	v_mov_b32_e32 v3, v0
	v_mov_b32_e32 v4, v0
	v_mov_b32_e32 v5, v0
	v_mov_b32_e32 v6, v0
	v_mov_b32_e32 v7, v0
	v_mov_b32_e32 v8, v0
	v_mov_b32_e32 v9, v0
	v_mov_b32_e32 v10, v0
	v_mov_b32_e32 v11, v0
	v_mov_b32_e32 v12, v0
	v_mov_b32_e32 v13, v0
	v_mov_b32_e32 v14, v0
	v_mov_b32_e32 v15, v0
	v_mov_b32_e32 v16, v0
	v_mov_b32_e32 v17, v0
	v_mov_b32_e32 v18, v0
	v_mov_b32_e32 v19, v0
	v_mov_b32_e32 v20, v0
	v_mov_b32_e32 v21, v0
	v_mov_b32_e32 v22, v0
	v_mov_b32_e32 v23, v0
	v_mov_b32_e32 v24, v0
	v_mov_b32_e32 v25, v0
	v_mov_b32_e32 v26, v0
	v_mov_b32_e32 v27, v0
	v_mov_b32_e32 v28, v0
	v_mov_b32_e32 v29, v0
	v_mov_b32_e32 v30, v0
	v_mov_b32_e32 v31, v0
	v_mov_b32_e32 v32, v0
	v_mov_b32_e32 v33, v0
	v_mov_b32_e32 v34, v0
	v_mov_b32_e32 v35, v0
	v_mov_b32_e32 v36, v0
	v_mov_b32_e32 v37, v0
	v_mov_b32_e32 v38, v0
	v_mov_b32_e32 v39, v0
	v_mov_b32_e32 v40, v0
	v_mov_b32_e32 v41, v0
	v_mov_b32_e32 v42, v0
	v_mov_b32_e32 v43, v0
	v_mov_b32_e32 v44, v0
	v_mov_b32_e32 v45, v0
	v_mov_b32_e32 v46, v0
	v_mov_b32_e32 v47, v0
	v_mov_b32_e32 v48, v0
	v_mov_b32_e32 v49, v0
	v_mov_b32_e32 v50, v0
	v_mov_b32_e32 v51, v0
	v_mov_b32_e32 v52, v0
	v_mov_b32_e32 v53, v0
	v_mov_b32_e32 v54, v0
	v_mov_b32_e32 v55, v0
	v_mov_b32_e32 v56, v0
	v_mov_b32_e32 v57, v0
	v_mov_b32_e32 v58, v0
	v_mov_b32_e32 v59, v0
	v_mov_b32_e32 v60, v0
	v_mov_b32_e32 v61, v0
	v_mov_b32_e32 v62, v0
	v_mov_b32_e32 v63, v0
	v_mov_b32_e32 v64, v0
	v_mov_b32_e32 v65, v0
	v_mov_b32_e32 v66, v0
	v_mov_b32_e32 v67, v0
	v_mov_b32_e32 v68, v0
	v_mov_b32_e32 v69, v0
	v_mov_b32_e32 v70, v0
	v_mov_b32_e32 v71, v0
	v_mov_b32_e32 v72, v0
	v_mov_b32_e32 v73, v0
	v_mov_b32_e32 v74, v0
	v_mov_b32_e32 v75, v0
	v_mov_b32_e32 v76, v0
	v_mov_b32_e32 v77, v0
	v_mov_b32_e32 v78, v0
	v_mov_b32_e32 v79, v0
	v_mov_b32_e32 v80, v0
	v_mov_b32_e32 v81, v0
	v_mov_b32_e32 v82, v0
	v_mov_b32_e32 v83, v0
	v_mov_b32_e32 v84, v0
	v_mov_b32_e32 v85, v0
	v_mov_b32_e32 v86, v0
	v_mov_b32_e32 v87, v0
	v_mov_b32_e32 v88, v0
	v_mov_b32_e32 v89, v0
	v_mov_b32_e32 v90, v0
	v_mov_b32_e32 v91, v0
	v_mov_b32_e32 v92, v0
	v_mov_b32_e32 v93, v0
	v_mov_b32_e32 v94, v0
	v_mov_b32_e32 v95, v0
	v_mov_b32_e32 v96, v0
	v_mov_b32_e32 v97, v0
	v_mov_b32_e32 v98, v0
	v_mov_b32_e32 v99, v0
	v_mov_b32_e32 v100, v0
	v_mov_b32_e32 v101, v0
	v_mov_b32_e32 v102, v0
	v_mov_b32_e32 v103, v0
	v_mov_b32_e32 v104, v0
	v_mov_b32_e32 v105, v0
	v_mov_b32_e32 v106, v0
	v_mov_b32_e32 v107, v0
	v_mov_b32_e32 v108, v0
	v_mov_b32_e32 v109, v0
	v_mov_b32_e32 v110, v0
	v_mov_b32_e32 v111, v0
	v_mov_b32_e32 v112, v0
	v_mov_b32_e32 v113, v0
	v_mov_b32_e32 v114, v0
	v_mov_b32_e32 v115, v0
	v_mov_b32_e32 v116, v0
	v_mov_b32_e32 v117, v0
	v_mov_b32_e32 v118, v0
	v_mov_b32_e32 v119, v0
	v_mov_b32_e32 v120, v0
	v_mov_b32_e32 v121, v0
	v_mov_b32_e32 v122, v0
	v_mov_b32_e32 v123, v0
	v_mov_b32_e32 v124, v0
	v_mov_b32_e32 v125, v0
	v_mov_b32_e32 v126, v0
	v_mov_b32_e32 v127, v0
	v_readfirstlane_b32 s74, v170
	v_readfirstlane_b32 s75, v171
	v_readfirstlane_b32 s76, v172
	v_readfirstlane_b32 s77, v173
	v_readfirstlane_b32 s32, v168
	s_nop 3
	s_sub_u32 s74, s74, s32
	s_subb_u32 s75, s75, 0
	s_add_u32 s74, s74, s4
	s_addc_u32 s75, s75, s5
	s_sub_u32 s76, s76, s32
	s_subb_u32 s77, s77, 0
	s_add_u32 s76, s76, s4
	s_addc_u32 s77, s77, s5
	v_add_u32_e32 v240, 0x80, v168
	v_add_u32_e32 v241, 0x20080, v168
	v_add_u32_e32 v242, 0x40080, v168
	v_add_u32_e32 v243, 0x60080, v168
.LBB0_202:
	s_add_i32 s8, s7, 0x10000
	s_and_b32 s9, s8, 0x10000
	s_add_i32 s9, s23, s9
	s_mov_b32 m0, s9
	s_nop 0
	global_load_lds_dwordx4 v240, s[74:75]
	s_add_i32 m0, s9, 0x8000
	s_nop 0
	global_load_lds_dwordx4 v240, s[76:77]
	s_add_i32 m0, s9, 0x2000
	s_nop 0
	global_load_lds_dwordx4 v241, s[74:75]
	s_add_i32 m0, s9, 0xa000
	s_nop 0
	global_load_lds_dwordx4 v241, s[76:77]
	s_add_i32 m0, s9, 0x4000
	s_nop 0
	global_load_lds_dwordx4 v242, s[74:75]
	s_add_i32 m0, s9, 0xc000
	s_nop 0
	global_load_lds_dwordx4 v242, s[76:77]
	s_add_i32 m0, s9, 0x6000
	s_nop 0
	global_load_lds_dwordx4 v243, s[74:75]
	s_add_i32 m0, s9, 0xe000
	s_and_b32 s7, s7, 0x10000
	s_nop 0
	global_load_lds_dwordx4 v243, s[76:77]
	s_add_u32 s74, s74, 0x80
	s_addc_u32 s75, s75, 0
	s_add_u32 s76, s76, 0x80
	s_addc_u32 s77, s77, 0
	s_add_i32 s7, s7, 16
	v_add3_u32 v132, s7, v183, v154
	v_add3_u32 v155, s7, v184, v154
	v_add_u32_e32 v169, v155, v159
	v_add_u32_e32 v193, v132, v159
	ds_read_b128 v[128:131], v169 offset:32768
	ds_read_b128 v[174:177], v193
	ds_read_b128 v[194:197], v169 offset:36864
	ds_read_b128 v[198:201], v193 offset:4096
	ds_read_b128 v[204:207], v193 offset:8192
	ds_read_b128 v[208:211], v193 offset:12288
	s_waitcnt lgkmcnt(0)
	v_mfma_f32_32x32x16_bf16 v[112:127], v[128:131], v[174:177], v[112:127]
	v_add_u32_e32 v169, v155, v161
	v_add_u32_e32 v178, v132, v161
	s_add_u32 s4, s4, 0x80
	s_addc_u32 s5, s5, 0
	s_cmpk_eq_i32 s4, 0x780
	s_mov_b32 s7, s8
	v_mfma_f32_32x32x16_bf16 v[96:111], v[128:131], v[198:201], v[96:111]
	v_mfma_f32_32x32x16_bf16 v[80:95], v[128:131], v[204:207], v[80:95]
	v_mfma_f32_32x32x16_bf16 v[64:79], v[128:131], v[208:211], v[64:79]
	v_mfma_f32_32x32x16_bf16 v[48:63], v[194:197], v[174:177], v[48:63]
	v_mfma_f32_32x32x16_bf16 v[32:47], v[194:197], v[198:201], v[32:47]
	v_mfma_f32_32x32x16_bf16 v[16:31], v[194:197], v[204:207], v[16:31]
	v_mfma_f32_32x32x16_bf16 v[0:15], v[194:197], v[208:211], v[0:15]
	ds_read_b128 v[128:131], v169 offset:32768
	ds_read_b128 v[174:177], v178
	ds_read_b128 v[194:197], v169 offset:36864
	ds_read_b128 v[198:201], v178 offset:4096
	ds_read_b128 v[204:207], v178 offset:8192
	ds_read_b128 v[208:211], v178 offset:12288
	v_add_u32_e32 v169, v155, v180
	v_add_u32_e32 v178, v132, v180
	v_add_u32_e32 v155, v155, v181
	v_add_u32_e32 v132, v132, v181
	s_waitcnt lgkmcnt(0)
; #define MFMA(a, b, c) __builtin_amdgcn_mfma_f32_32x32x16_bf16((a), (b), (c), 0, 0, 0)
; #define G_BARRIER() { asm volatile("s_waitcnt vmcnt(0) lgkmcnt(0)" ::: "memory"); __builtin_amdgcn_s_barrier(); asm volatile("" ::: "memory"); }
;     ...
; #pragma unroll
;             for (int ks = 0; ks < 4; ++ks) {
;                 bf16x8 wfr[2], afr[TB];
; #pragma unroll
;                 for (int fb = 0; fb < 2; ++fb) wfr[fb] = *(const bf16x8*)(sw + fb * 4096 + koff[ks]);
; #pragma unroll
;                 for (int tb = 0; tb < TB; ++tb) afr[tb] = *(const bf16x8*)(sa + tb * 4096 + koff[ks]);
; #pragma unroll
;                 for (int fb = 0; fb < 2; ++fb)
; #pragma unroll
;                     for (int tb = 0; tb < TB; ++tb) acc[fb][tb] = MFMA(wfr[fb], afr[tb], acc[fb][tb]);
;             }
;             G_BARRIER();
	v_mfma_f32_32x32x16_bf16 v[112:127], v[128:131], v[174:177], v[112:127]
	v_mfma_f32_32x32x16_bf16 v[96:111], v[128:131], v[198:201], v[96:111]
	v_mfma_f32_32x32x16_bf16 v[80:95], v[128:131], v[204:207], v[80:95]
	v_mfma_f32_32x32x16_bf16 v[64:79], v[128:131], v[208:211], v[64:79]
	v_mfma_f32_32x32x16_bf16 v[48:63], v[194:197], v[174:177], v[48:63]
	v_mfma_f32_32x32x16_bf16 v[32:47], v[194:197], v[198:201], v[32:47]
	v_mfma_f32_32x32x16_bf16 v[16:31], v[194:197], v[204:207], v[16:31]
	v_mfma_f32_32x32x16_bf16 v[0:15], v[194:197], v[208:211], v[0:15]
	ds_read_b128 v[128:131], v169 offset:32768
	ds_read_b128 v[174:177], v178
	ds_read_b128 v[194:197], v169 offset:36864
	ds_read_b128 v[198:201], v178 offset:4096
	ds_read_b128 v[204:207], v178 offset:8192
	ds_read_b128 v[208:211], v178 offset:12288
	s_waitcnt lgkmcnt(0)
	v_mfma_f32_32x32x16_bf16 v[112:127], v[128:131], v[174:177], v[112:127]
	v_mfma_f32_32x32x16_bf16 v[96:111], v[128:131], v[198:201], v[96:111]
	v_mfma_f32_32x32x16_bf16 v[80:95], v[128:131], v[204:207], v[80:95]
	v_mfma_f32_32x32x16_bf16 v[64:79], v[128:131], v[208:211], v[64:79]
	v_mfma_f32_32x32x16_bf16 v[48:63], v[194:197], v[174:177], v[48:63]
	v_mfma_f32_32x32x16_bf16 v[32:47], v[194:197], v[198:201], v[32:47]
	v_mfma_f32_32x32x16_bf16 v[16:31], v[194:197], v[204:207], v[16:31]
	v_mfma_f32_32x32x16_bf16 v[0:15], v[194:197], v[208:211], v[0:15]
	ds_read_b128 v[128:131], v155 offset:32768
	ds_read_b128 v[174:177], v132
	ds_read_b128 v[194:197], v155 offset:36864
	ds_read_b128 v[198:201], v132 offset:4096
	ds_read_b128 v[204:207], v132 offset:8192
	ds_read_b128 v[208:211], v132 offset:12288
	s_waitcnt vmcnt(0) lgkmcnt(0)
	s_barrier
	s_waitcnt lgkmcnt(0)
	v_mfma_f32_32x32x16_bf16 v[112:127], v[128:131], v[174:177], v[112:127]
	v_mfma_f32_32x32x16_bf16 v[96:111], v[128:131], v[198:201], v[96:111]
	v_mfma_f32_32x32x16_bf16 v[80:95], v[128:131], v[204:207], v[80:95]
	v_mfma_f32_32x32x16_bf16 v[64:79], v[128:131], v[208:211], v[64:79]
	v_mfma_f32_32x32x16_bf16 v[48:63], v[194:197], v[174:177], v[48:63]
	v_mfma_f32_32x32x16_bf16 v[32:47], v[194:197], v[198:201], v[32:47]
	v_mfma_f32_32x32x16_bf16 v[16:31], v[194:197], v[204:207], v[16:31]
	v_mfma_f32_32x32x16_bf16 v[0:15], v[194:197], v[208:211], v[0:15]
	s_cbranch_scc0 .LBB0_202
; #define GAS __attribute__((address_space(1)))
; #define MFMA(a, b, c) __builtin_amdgcn_mfma_f32_32x32x16_bf16((a), (b), (c), 0, 0, 0)
; #define G_BARRIER() { asm volatile("s_waitcnt vmcnt(0) lgkmcnt(0)" ::: "memory"); __builtin_amdgcn_s_barrier(); asm volatile("" ::: "memory"); }
;     ...
;         for (int kt = 0; kt < nk; ++kt) {
;             if (kt + 1 < nk) { G_DMA(kt + 1, (kt + 1) & 1); }
;             const unsigned char* sa = lds + (kt & 1) * 65536 + (wt * 32 * TB + r) * 128;
;             const unsigned char* sw = lds + (kt & 1) * 65536 + 32768 + (wf * 64 + r) * 128;
; #pragma unroll
;             for (int ks = 0; ks < 4; ++ks) {
;                 bf16x8 wfr[2], afr[TB];
; #pragma unroll
;                 for (int fb = 0; fb < 2; ++fb) wfr[fb] = *(const bf16x8*)(sw + fb * 4096 + koff[ks]);
; #pragma unroll
;                 for (int tb = 0; tb < TB; ++tb) afr[tb] = *(const bf16x8*)(sa + tb * 4096 + koff[ks]);
; #pragma unroll
;                 for (int fb = 0; fb < 2; ++fb)
; #pragma unroll
;                     for (int tb = 0; tb < TB; ++tb) acc[fb][tb] = MFMA(wfr[fb], afr[tb], acc[fb][tb]);
;             }
;             G_BARRIER();
;         }
;         const int un = u + nslots;
;         if (un < nloc) {
;             Ag = (const GAS bf16_t*)(A + (size_t)(xcd + nx * (un / Ntiles)) * RM * K) + dsrc; Wg = (const GAS bf16_t*)(Wt + (size_t)(un % Ntiles) * 256 * K) + dsrc;
;             G_DMA(0, 0);
;         }
	v_add_u32_e32 v132, v189, v159
	ds_read_b128 v[128:131], v132
	v_add_u32_e32 v155, v188, v159
	ds_read_b128 v[174:177], v155
	ds_read_b128 v[194:197], v155 offset:4096
	ds_read_b128 v[198:201], v155 offset:8192
	ds_read_b128 v[204:207], v155 offset:12288
	v_add_u32_e32 v155, v188, v161
	s_add_i32 s24, s6, s0
	s_cmp_ge_i32 s24, s1
	s_waitcnt lgkmcnt(0)
	v_mfma_f32_32x32x16_bf16 v[112:127], v[128:131], v[174:177], v[112:127]
	s_cselect_b64 s[96:97], -1, 0
	s_cmp_lt_i32 s24, s1
	v_mfma_f32_32x32x16_bf16 v[96:111], v[128:131], v[194:197], v[96:111]
	v_mfma_f32_32x32x16_bf16 v[80:95], v[128:131], v[198:201], v[80:95]
	v_mfma_f32_32x32x16_bf16 v[64:79], v[128:131], v[204:207], v[64:79]
	ds_read_b128 v[128:131], v132 offset:4096
	v_add_u32_e32 v132, v189, v161
	s_waitcnt lgkmcnt(0)
	v_mfma_f32_32x32x16_bf16 v[48:63], v[128:131], v[174:177], v[48:63]
	ds_read_b128 v[174:177], v155
	v_mfma_f32_32x32x16_bf16 v[32:47], v[128:131], v[194:197], v[32:47]
	ds_read_b128 v[194:197], v155 offset:4096
	v_mfma_f32_32x32x16_bf16 v[16:31], v[128:131], v[198:201], v[16:31]
	ds_read_b128 v[198:201], v155 offset:8192
	v_mfma_f32_32x32x16_bf16 v[0:15], v[128:131], v[204:207], v[0:15]
	ds_read_b128 v[128:131], v132
	ds_read_b128 v[204:207], v155 offset:12288
	v_add_u32_e32 v155, v188, v180
	s_waitcnt lgkmcnt(0)
	v_mfma_f32_32x32x16_bf16 v[112:127], v[128:131], v[174:177], v[112:127]
	v_mfma_f32_32x32x16_bf16 v[96:111], v[128:131], v[194:197], v[96:111]
	v_mfma_f32_32x32x16_bf16 v[80:95], v[128:131], v[198:201], v[80:95]
	v_mfma_f32_32x32x16_bf16 v[64:79], v[128:131], v[204:207], v[64:79]
	ds_read_b128 v[128:131], v132 offset:4096
	v_add_u32_e32 v132, v189, v180
	s_waitcnt lgkmcnt(0)
	v_mfma_f32_32x32x16_bf16 v[48:63], v[128:131], v[174:177], v[48:63]
	ds_read_b128 v[174:177], v155
	v_mfma_f32_32x32x16_bf16 v[32:47], v[128:131], v[194:197], v[32:47]
	ds_read_b128 v[194:197], v155 offset:4096
	v_mfma_f32_32x32x16_bf16 v[16:31], v[128:131], v[198:201], v[16:31]
	ds_read_b128 v[198:201], v155 offset:8192
	v_mfma_f32_32x32x16_bf16 v[0:15], v[128:131], v[204:207], v[0:15]
	ds_read_b128 v[128:131], v132
	ds_read_b128 v[204:207], v155 offset:12288
	v_add_u32_e32 v155, v188, v181
	s_waitcnt lgkmcnt(0)
	v_mfma_f32_32x32x16_bf16 v[112:127], v[128:131], v[174:177], v[112:127]
	v_mfma_f32_32x32x16_bf16 v[96:111], v[128:131], v[194:197], v[96:111]
	v_mfma_f32_32x32x16_bf16 v[80:95], v[128:131], v[198:201], v[80:95]
	v_mfma_f32_32x32x16_bf16 v[64:79], v[128:131], v[204:207], v[64:79]
	ds_read_b128 v[128:131], v132 offset:4096
	v_add_u32_e32 v132, v189, v181
	s_waitcnt lgkmcnt(0)
	v_mfma_f32_32x32x16_bf16 v[48:63], v[128:131], v[174:177], v[48:63]
	ds_read_b128 v[174:177], v155
	v_mfma_f32_32x32x16_bf16 v[32:47], v[128:131], v[194:197], v[32:47]
	ds_read_b128 v[194:197], v155 offset:4096
	v_mfma_f32_32x32x16_bf16 v[16:31], v[128:131], v[198:201], v[16:31]
	ds_read_b128 v[198:201], v155 offset:8192
	v_mfma_f32_32x32x16_bf16 v[0:15], v[128:131], v[204:207], v[0:15]
	ds_read_b128 v[128:131], v132
	ds_read_b128 v[204:207], v155 offset:12288
	s_waitcnt lgkmcnt(0)
	v_mfma_f32_32x32x16_bf16 v[112:127], v[128:131], v[174:177], v[112:127]
	v_mfma_f32_32x32x16_bf16 v[96:111], v[128:131], v[194:197], v[96:111]
	v_mfma_f32_32x32x16_bf16 v[80:95], v[128:131], v[198:201], v[80:95]
	v_mfma_f32_32x32x16_bf16 v[64:79], v[128:131], v[204:207], v[64:79]
	ds_read_b128 v[128:131], v132 offset:4096
	s_waitcnt vmcnt(0) lgkmcnt(0)
	s_barrier
	s_waitcnt lgkmcnt(0)
	v_mfma_f32_32x32x16_bf16 v[48:63], v[128:131], v[174:177], v[48:63]
	v_mfma_f32_32x32x16_bf16 v[32:47], v[128:131], v[194:197], v[32:47]
	v_mfma_f32_32x32x16_bf16 v[16:31], v[128:131], v[198:201], v[16:31]
	v_mfma_f32_32x32x16_bf16 v[0:15], v[128:131], v[204:207], v[0:15]
	s_cbranch_scc0 .LBB0_205
	s_mul_hi_i32 s4, s24, 0x66666667
	s_lshr_b32 s5, s4, 31
	s_ashr_i32 s4, s4, 2
	s_add_i32 s7, s4, s5
	s_lshl_b32 s4, s7, s68
	s_add_i32 s4, s4, s69
	s_ashr_i32 s5, s4, 31
	s_lshl_b64 s[4:5], s[4:5], 19
	s_add_u32 s4, s60, s4
	s_mul_i32 s7, s7, 10
	s_addc_u32 s5, s61, s5
	s_sub_i32 s8, s24, s7
	s_ashr_i32 s9, s8, 31
	s_lshl_b64 s[8:9], s[8:9], 19
	s_mov_b32 m0, s23
	v_mov_b32_e32 v169, v133
	s_add_u32 s8, s62, s8
	v_lshl_add_u64 v[170:171], s[4:5], 0, v[168:169]
	s_addc_u32 s9, s63, s9
	global_load_lds_dwordx4 v168, s[4:5]
	s_add_i32 m0, s23, 0x8000
	v_lshl_add_u64 v[172:173], s[8:9], 0, v[168:169]
	global_load_lds_dwordx4 v168, s[8:9]
	v_lshl_add_u64 v[128:129], v[170:171], 0, s[66:67]
	s_add_i32 m0, s23, 0x2000
	s_nop 0
	global_load_lds_dwordx4 v[128:129], off
	v_lshl_add_u64 v[128:129], v[172:173], 0, s[66:67]
	s_add_i32 m0, s23, 0xa000
	s_nop 0
	global_load_lds_dwordx4 v[128:129], off
	v_lshl_add_u64 v[128:129], v[170:171], 0, s[70:71]
	s_add_i32 m0, s23, 0x4000
	s_nop 0
	global_load_lds_dwordx4 v[128:129], off
	v_lshl_add_u64 v[128:129], v[172:173], 0, s[70:71]
	s_add_i32 m0, s23, 0xc000
	s_nop 0
	global_load_lds_dwordx4 v[128:129], off
	v_lshl_add_u64 v[128:129], v[170:171], 0, s[72:73]
	s_add_i32 m0, s23, 0x6000
	s_nop 0
	global_load_lds_dwordx4 v[128:129], off
	v_lshl_add_u64 v[128:129], v[172:173], 0, s[72:73]
	s_add_i32 m0, s23, 0xe000
	s_nop 0
	global_load_lds_dwordx4 v[128:129], off

; #define G_BARRIER() { asm volatile("s_waitcnt vmcnt(0) lgkmcnt(0)" ::: "memory"); __builtin_amdgcn_s_barrier(); asm volatile("" ::: "memory"); }
;     ...
; #pragma unroll
;         for (int a = 0; a < 2; ++a)
; #pragma unroll
;             for (int b = 0; b < TB; ++b)
; #pragma unroll
;                 for (int i = 0; i < 16; ++i) acc[a][b][i] = 0.f;
;         G_BARRIER();
.LBB0_481:
	s_waitcnt vmcnt(0) lgkmcnt(0)
	s_barrier
	v_mov_b32_e32 v0, 0
	s_mov_b32 s18, s89
	s_mov_b32 s6, 0
	s_mov_b64 s[4:5], 0
	v_mov_b32_e32 v1, v0
	v_mov_b32_e32 v2, v0
	v_mov_b32_e32 v3, v0
	v_mov_b32_e32 v4, v0
	v_mov_b32_e32 v5, v0
	v_mov_b32_e32 v6, v0
	v_mov_b32_e32 v7, v0
	v_mov_b32_e32 v8, v0
	v_mov_b32_e32 v9, v0
	v_mov_b32_e32 v10, v0
	v_mov_b32_e32 v11, v0
	v_mov_b32_e32 v12, v0
	v_mov_b32_e32 v13, v0
	v_mov_b32_e32 v14, v0
	v_mov_b32_e32 v15, v0
	v_mov_b32_e32 v16, v0
	v_mov_b32_e32 v17, v0
	v_mov_b32_e32 v18, v0
	v_mov_b32_e32 v19, v0
	v_mov_b32_e32 v20, v0
	v_mov_b32_e32 v21, v0
	v_mov_b32_e32 v22, v0
	v_mov_b32_e32 v23, v0
	v_mov_b32_e32 v24, v0
	v_mov_b32_e32 v25, v0
	v_mov_b32_e32 v26, v0
	v_mov_b32_e32 v27, v0
	v_mov_b32_e32 v28, v0
	v_mov_b32_e32 v29, v0
	v_mov_b32_e32 v30, v0
	v_mov_b32_e32 v31, v0
	v_mov_b32_e32 v32, v0
	v_mov_b32_e32 v33, v0
	v_mov_b32_e32 v34, v0
	v_mov_b32_e32 v35, v0
	v_mov_b32_e32 v36, v0
	v_mov_b32_e32 v37, v0
	v_mov_b32_e32 v38, v0
	v_mov_b32_e32 v39, v0
	v_mov_b32_e32 v40, v0
	v_mov_b32_e32 v41, v0
	v_mov_b32_e32 v42, v0
	v_mov_b32_e32 v43, v0
	v_mov_b32_e32 v44, v0
	v_mov_b32_e32 v45, v0
	v_mov_b32_e32 v46, v0
	v_mov_b32_e32 v47, v0
	v_mov_b32_e32 v48, v0
	v_mov_b32_e32 v49, v0
	v_mov_b32_e32 v50, v0
	v_mov_b32_e32 v51, v0
	v_mov_b32_e32 v52, v0
	v_mov_b32_e32 v53, v0
	v_mov_b32_e32 v54, v0
	v_mov_b32_e32 v55, v0
	v_mov_b32_e32 v56, v0
	v_mov_b32_e32 v57, v0
	v_mov_b32_e32 v58, v0
	v_mov_b32_e32 v59, v0
	v_mov_b32_e32 v60, v0
	v_mov_b32_e32 v61, v0
	v_mov_b32_e32 v62, v0
	v_mov_b32_e32 v63, v0
	v_readfirstlane_b32 s76, v86
	v_readfirstlane_b32 s77, v87
	v_readfirstlane_b32 s78, v88
	v_readfirstlane_b32 s79, v89
	v_readfirstlane_b32 s32, v84
	s_nop 3
	s_sub_u32 s76, s76, s32
	s_subb_u32 s77, s77, 0
	s_add_u32 s76, s76, s4
	s_addc_u32 s77, s77, s5
	s_sub_u32 s78, s78, s32
	s_subb_u32 s79, s79, 0
	s_add_u32 s78, s78, s4
	s_addc_u32 s79, s79, s5
	v_add_u32_e32 v240, 0x80, v84
	v_add_u32_e32 v241, 0x20080, v84
	v_add_u32_e32 v242, 0x40080, v84
	v_add_u32_e32 v243, 0x60080, v84
; #define GAS __attribute__((address_space(1)))
; #define MFMA(a, b, c) __builtin_amdgcn_mfma_f32_32x32x16_bf16((a), (b), (c), 0, 0, 0)
; #define G_BARRIER() { asm volatile("s_waitcnt vmcnt(0) lgkmcnt(0)" ::: "memory"); __builtin_amdgcn_s_barrier(); asm volatile("" ::: "memory"); }
;     ...
;         for (int kt = 0; kt < nk; ++kt) {
;             if (kt + 1 < nk) { G_DMA(kt + 1, (kt + 1) & 1); }
;             const unsigned char* sa = lds + (kt & 1) * 65536 + (wt * 32 * TB + r) * 128;
;             const unsigned char* sw = lds + (kt & 1) * 65536 + 32768 + (wf * 64 + r) * 128;
; #pragma unroll
;             for (int ks = 0; ks < 4; ++ks) {
;                 bf16x8 wfr[2], afr[TB];
; #pragma unroll
;                 for (int fb = 0; fb < 2; ++fb) wfr[fb] = *(const bf16x8*)(sw + fb * 4096 + koff[ks]);
; #pragma unroll
;                 for (int tb = 0; tb < TB; ++tb) afr[tb] = *(const bf16x8*)(sa + tb * 4096 + koff[ks]);
; #pragma unroll
;                 for (int fb = 0; fb < 2; ++fb)
; #pragma unroll
;                     for (int tb = 0; tb < TB; ++tb) acc[fb][tb] = MFMA(wfr[fb], afr[tb], acc[fb][tb]);
;             }
;             G_BARRIER();
;         }
;         const int un = u + nslots;
;         if (un < nloc) {
;             Ag = (const GAS bf16_t*)(A + (size_t)(xcd + nx * (un / Ntiles)) * RM * K) + dsrc; Wg = (const GAS bf16_t*)(Wt + (size_t)(un % Ntiles) * 256 * K) + dsrc;
;             G_DMA(0, 0);
;         }
.LBB0_482:
	s_add_i32 s7, s6, 0x10000
	s_and_b32 s6, s6, 0x10000
	s_and_b32 s19, s7, 0x10000
	s_add_i32 s6, s6, 16
	s_add_i32 s19, s16, s19
	v_add3_u32 v64, s6, v119, v120
	v_add3_u32 v85, s6, v121, v120
	s_add_i32 s6, s19, 0x8000
	s_mov_b32 m0, s19
	s_nop 0
	global_load_lds_dwordx4 v240, s[76:77]
	s_mov_b32 m0, s6
	s_nop 0
	global_load_lds_dwordx4 v240, s[78:79]
	s_add_i32 m0, s19, 0x2000
	s_mov_b64 s[90:91], 0x40080
	s_nop 0
	global_load_lds_dwordx4 v241, s[76:77]
	s_add_i32 m0, s19, 0xa000
	s_mov_b64 s[92:93], 0x60080
	s_nop 0
	global_load_lds_dwordx4 v241, s[78:79]
	s_add_i32 m0, s19, 0xc000
	s_nop 0
	global_load_lds_dwordx4 v242, s[78:79]
	s_add_i32 m0, s19, 0xe000
	v_add_u32_e32 v102, v85, v114
	s_nop 0
	global_load_lds_dwordx4 v243, s[78:79]
	s_add_u32 s76, s76, 0x80
	s_addc_u32 s77, s77, 0
	s_add_u32 s78, s78, 0x80
	s_addc_u32 s79, s79, 0
	v_add_u32_e32 v103, v64, v114
	ds_read_b128 v[90:93], v102 offset:32768
	ds_read_b128 v[94:97], v103
	ds_read_b128 v[98:101], v103 offset:4096
	ds_read_b128 v[102:105], v102 offset:36864
	s_waitcnt lgkmcnt(0)
	v_mfma_f32_32x32x16_bf16 v[48:63], v[90:93], v[94:97], v[48:63]
	v_add_u32_e32 v106, v85, v115
	v_add_u32_e32 v107, v64, v115
	s_add_u32 s4, s4, 0x80
	s_addc_u32 s5, s5, 0
	s_cmpk_eq_i32 s4, 0x780
	s_mov_b32 s6, s7
	v_mfma_f32_32x32x16_bf16 v[32:47], v[90:93], v[98:101], v[32:47]
	v_mfma_f32_32x32x16_bf16 v[16:31], v[102:105], v[94:97], v[16:31]
	v_mfma_f32_32x32x16_bf16 v[0:15], v[102:105], v[98:101], v[0:15]
	ds_read_b128 v[90:93], v106 offset:32768
	ds_read_b128 v[94:97], v107
	ds_read_b128 v[98:101], v107 offset:4096
	ds_read_b128 v[102:105], v106 offset:36864
	v_add_u32_e32 v106, v85, v116
	v_add_u32_e32 v107, v64, v116
	v_add_u32_e32 v85, v85, v117
	v_add_u32_e32 v64, v64, v117
	s_waitcnt lgkmcnt(0)
	v_mfma_f32_32x32x16_bf16 v[48:63], v[90:93], v[94:97], v[48:63]
	v_mfma_f32_32x32x16_bf16 v[32:47], v[90:93], v[98:101], v[32:47]
	v_mfma_f32_32x32x16_bf16 v[16:31], v[102:105], v[94:97], v[16:31]
	v_mfma_f32_32x32x16_bf16 v[0:15], v[102:105], v[98:101], v[0:15]
	ds_read_b128 v[90:93], v106 offset:32768
	ds_read_b128 v[94:97], v107
	ds_read_b128 v[98:101], v107 offset:4096
	ds_read_b128 v[102:105], v106 offset:36864
	s_waitcnt lgkmcnt(0)
	v_mfma_f32_32x32x16_bf16 v[48:63], v[90:93], v[94:97], v[48:63]
	v_mfma_f32_32x32x16_bf16 v[32:47], v[90:93], v[98:101], v[32:47]
	v_mfma_f32_32x32x16_bf16 v[16:31], v[102:105], v[94:97], v[16:31]
	v_mfma_f32_32x32x16_bf16 v[0:15], v[102:105], v[98:101], v[0:15]
	ds_read_b128 v[90:93], v85 offset:32768
	ds_read_b128 v[94:97], v64
	ds_read_b128 v[98:101], v64 offset:4096
	ds_read_b128 v[102:105], v85 offset:36864
	s_waitcnt vmcnt(0) lgkmcnt(0)
	s_barrier
	s_waitcnt lgkmcnt(0)
	v_mfma_f32_32x32x16_bf16 v[48:63], v[90:93], v[94:97], v[48:63]
	v_mfma_f32_32x32x16_bf16 v[32:47], v[90:93], v[98:101], v[32:47]
	v_mfma_f32_32x32x16_bf16 v[16:31], v[102:105], v[94:97], v[16:31]
	v_mfma_f32_32x32x16_bf16 v[0:15], v[102:105], v[98:101], v[0:15]
	s_cbranch_scc0 .LBB0_482
	v_add_u32_e32 v64, v125, v114
	ds_read_b128 v[90:93], v64
	v_add_u32_e32 v85, v124, v114
	ds_read_b128 v[94:97], v85
	ds_read_b128 v[98:101], v85 offset:4096
	ds_read_b128 v[102:105], v64 offset:4096
	v_add_u32_e32 v64, v125, v115
	v_add_u32_e32 v85, v124, v115
	s_waitcnt lgkmcnt(0)
	v_mfma_f32_32x32x16_bf16 v[16:31], v[102:105], v[94:97], v[16:31]
	s_add_i32 s89, s18, s25
	s_cmp_ge_i32 s89, s26
	s_cselect_b64 s[6:7], -1, 0
	s_cmp_lt_i32 s89, s26
	v_mfma_f32_32x32x16_bf16 v[48:63], v[90:93], v[94:97], v[48:63]
	v_mfma_f32_32x32x16_bf16 v[32:47], v[90:93], v[98:101], v[32:47]
	ds_read_b128 v[90:93], v64
	v_mfma_f32_32x32x16_bf16 v[0:15], v[102:105], v[98:101], v[0:15]
	ds_read_b128 v[94:97], v85
	ds_read_b128 v[98:101], v85 offset:4096
	ds_read_b128 v[102:105], v64 offset:4096
	v_add_u32_e32 v64, v125, v116
	v_add_u32_e32 v85, v124, v116
	s_waitcnt lgkmcnt(0)
	v_mfma_f32_32x32x16_bf16 v[48:63], v[90:93], v[94:97], v[48:63]
	v_mfma_f32_32x32x16_bf16 v[32:47], v[90:93], v[98:101], v[32:47]
	ds_read_b128 v[90:93], v64
	v_mfma_f32_32x32x16_bf16 v[16:31], v[102:105], v[94:97], v[16:31]
	v_mfma_f32_32x32x16_bf16 v[0:15], v[102:105], v[98:101], v[0:15]
	ds_read_b128 v[94:97], v85
	ds_read_b128 v[98:101], v85 offset:4096
	ds_read_b128 v[102:105], v64 offset:4096
	v_add_u32_e32 v64, v125, v117
	v_add_u32_e32 v85, v124, v117
	s_waitcnt lgkmcnt(0)
	v_mfma_f32_32x32x16_bf16 v[48:63], v[90:93], v[94:97], v[48:63]
	v_mfma_f32_32x32x16_bf16 v[32:47], v[90:93], v[98:101], v[32:47]
	ds_read_b128 v[90:93], v64
	v_mfma_f32_32x32x16_bf16 v[16:31], v[102:105], v[94:97], v[16:31]
	v_mfma_f32_32x32x16_bf16 v[0:15], v[102:105], v[98:101], v[0:15]
	ds_read_b128 v[94:97], v85
	ds_read_b128 v[98:101], v85 offset:4096
	ds_read_b128 v[102:105], v64 offset:4096
	s_waitcnt vmcnt(0) lgkmcnt(0)
	s_barrier
	s_waitcnt lgkmcnt(0)
	v_mfma_f32_32x32x16_bf16 v[48:63], v[90:93], v[94:97], v[48:63]
	v_mfma_f32_32x32x16_bf16 v[32:47], v[90:93], v[98:101], v[32:47]
	v_mfma_f32_32x32x16_bf16 v[16:31], v[102:105], v[94:97], v[16:31]
	v_mfma_f32_32x32x16_bf16 v[0:15], v[102:105], v[98:101], v[0:15]
	s_cbranch_scc0 .LBB0_485
	s_ashr_i32 s4, s89, 31
	s_lshr_b32 s4, s4, 30
	s_add_i32 s19, s89, s4
	s_ashr_i32 s4, s19, 2
	s_lshl_b32 s4, s4, s22
	s_add_i32 s4, s4, s24
	s_ashr_i32 s5, s4, 31
	s_lshl_b64 s[4:5], s[4:5], 18
	s_add_u32 s4, s1, s4
	s_addc_u32 s5, s3, s5
	s_and_b32 s19, s19, -4
	s_sub_i32 s90, s89, s19
	s_ashr_i32 s91, s90, 31
	s_lshl_b64 s[90:91], s[90:91], 19
	s_mov_b32 m0, s16
	v_mov_b32_e32 v85, v65
	s_add_u32 s90, s20, s90
	v_lshl_add_u64 v[86:87], s[4:5], 0, v[84:85]
	s_addc_u32 s91, s21, s91
	global_load_lds_dwordx4 v84, s[4:5]
	s_mov_b32 m0, s84
	v_lshl_add_u64 v[88:89], s[90:91], 0, v[84:85]
	global_load_lds_dwordx4 v84, s[90:91]
	v_lshl_add_u64 v[90:91], v[86:87], 0, s[38:39]
	s_mov_b32 m0, s85
	s_nop 0
	global_load_lds_dwordx4 v[90:91], off
	v_lshl_add_u64 v[90:91], v[88:89], 0, s[38:39]
	s_mov_b32 m0, s86
	s_nop 0
	global_load_lds_dwordx4 v[90:91], off
	v_lshl_add_u64 v[90:91], v[88:89], 0, s[42:43]
	s_mov_b32 m0, s87
	s_nop 0
	global_load_lds_dwordx4 v[90:91], off
	v_lshl_add_u64 v[90:91], v[88:89], 0, s[44:45]
	s_mov_b32 m0, s88
	s_nop 0
	global_load_lds_dwordx4 v[90:91], off

; #define MFMA(a, b, c) __builtin_amdgcn_mfma_f32_32x32x16_bf16((a), (b), (c), 0, 0, 0)
; #define G_BARRIER() { asm volatile("s_waitcnt vmcnt(0) lgkmcnt(0)" ::: "memory"); __builtin_amdgcn_s_barrier(); asm volatile("" ::: "memory"); }
;     ...
; #pragma unroll
;         for (int a = 0; a < 2; ++a)
; #pragma unroll
;             for (int b = 0; b < TB; ++b)
; #pragma unroll
;                 for (int i = 0; i < 16; ++i) acc[a][b][i] = 0.f;
;         G_BARRIER();
;         for (int kt = 0; kt < nk; ++kt) {
;             if (kt + 1 < nk) { G_DMA(kt + 1, (kt + 1) & 1); }
;             const unsigned char* sa = lds + (kt & 1) * 65536 + (wt * 32 * TB + r) * 128;
;             const unsigned char* sw = lds + (kt & 1) * 65536 + 32768 + (wf * 64 + r) * 128;
; #pragma unroll
;             for (int ks = 0; ks < 4; ++ks) {
;                 bf16x8 wfr[2], afr[TB];
; #pragma unroll
;                 for (int fb = 0; fb < 2; ++fb) wfr[fb] = *(const bf16x8*)(sw + fb * 4096 + koff[ks]);
; #pragma unroll
;                 for (int tb = 0; tb < TB; ++tb) afr[tb] = *(const bf16x8*)(sa + tb * 4096 + koff[ks]);
; #pragma unroll
;                 for (int fb = 0; fb < 2; ++fb)
; #pragma unroll
;                     for (int tb = 0; tb < TB; ++tb) acc[fb][tb] = MFMA(wfr[fb], afr[tb], acc[fb][tb]);
;             }
;             G_BARRIER();
.LBB0_742:
	s_waitcnt vmcnt(0) lgkmcnt(0)
	s_barrier
	v_mov_b32_e32 v0, 0
	s_mov_b32 s1, s0
	s_mov_b32 s0, 0
	s_mov_b64 s[6:7], 0
	v_mov_b32_e32 v1, v0
	v_mov_b32_e32 v2, v0
	v_mov_b32_e32 v3, v0
	v_mov_b32_e32 v4, v0
	v_mov_b32_e32 v5, v0
	v_mov_b32_e32 v6, v0
	v_mov_b32_e32 v7, v0
	v_mov_b32_e32 v8, v0
	v_mov_b32_e32 v9, v0
	v_mov_b32_e32 v10, v0
	v_mov_b32_e32 v11, v0
	v_mov_b32_e32 v12, v0
	v_mov_b32_e32 v13, v0
	v_mov_b32_e32 v14, v0
	v_mov_b32_e32 v15, v0
	v_mov_b32_e32 v16, v0
	v_mov_b32_e32 v17, v0
	v_mov_b32_e32 v18, v0
	v_mov_b32_e32 v19, v0
	v_mov_b32_e32 v20, v0
	v_mov_b32_e32 v21, v0
	v_mov_b32_e32 v22, v0
	v_mov_b32_e32 v23, v0
	v_mov_b32_e32 v24, v0
	v_mov_b32_e32 v25, v0
	v_mov_b32_e32 v26, v0
	v_mov_b32_e32 v27, v0
	v_mov_b32_e32 v28, v0
	v_mov_b32_e32 v29, v0
	v_mov_b32_e32 v30, v0
	v_mov_b32_e32 v31, v0
	v_mov_b32_e32 v32, v0
	v_mov_b32_e32 v33, v0
	v_mov_b32_e32 v34, v0
	v_mov_b32_e32 v35, v0
	v_mov_b32_e32 v36, v0
	v_mov_b32_e32 v37, v0
	v_mov_b32_e32 v38, v0
	v_mov_b32_e32 v39, v0
	v_mov_b32_e32 v40, v0
	v_mov_b32_e32 v41, v0
	v_mov_b32_e32 v42, v0
	v_mov_b32_e32 v43, v0
	v_mov_b32_e32 v44, v0
	v_mov_b32_e32 v45, v0
	v_mov_b32_e32 v46, v0
	v_mov_b32_e32 v47, v0
	v_mov_b32_e32 v48, v0
	v_mov_b32_e32 v49, v0
	v_mov_b32_e32 v50, v0
	v_mov_b32_e32 v51, v0
	v_mov_b32_e32 v52, v0
	v_mov_b32_e32 v53, v0
	v_mov_b32_e32 v54, v0
	v_mov_b32_e32 v55, v0
	v_mov_b32_e32 v56, v0
	v_mov_b32_e32 v57, v0
	v_mov_b32_e32 v58, v0
	v_mov_b32_e32 v59, v0
	v_mov_b32_e32 v60, v0
	v_mov_b32_e32 v61, v0
	v_mov_b32_e32 v62, v0
	v_mov_b32_e32 v63, v0
	v_mov_b32_e32 v64, v0
	v_mov_b32_e32 v65, v0
	v_mov_b32_e32 v66, v0
	v_mov_b32_e32 v67, v0
	v_mov_b32_e32 v68, v0
	v_mov_b32_e32 v69, v0
	v_mov_b32_e32 v70, v0
	v_mov_b32_e32 v71, v0
	v_mov_b32_e32 v72, v0
	v_mov_b32_e32 v73, v0
	v_mov_b32_e32 v74, v0
	v_mov_b32_e32 v75, v0
	v_mov_b32_e32 v76, v0
	v_mov_b32_e32 v77, v0
	v_mov_b32_e32 v78, v0
	v_mov_b32_e32 v79, v0
	v_mov_b32_e32 v80, v0
	v_mov_b32_e32 v81, v0
	v_mov_b32_e32 v82, v0
	v_mov_b32_e32 v83, v0
	v_mov_b32_e32 v84, v0
	v_mov_b32_e32 v85, v0
	v_mov_b32_e32 v86, v0
	v_mov_b32_e32 v87, v0
	v_mov_b32_e32 v88, v0
	v_mov_b32_e32 v89, v0
	v_mov_b32_e32 v90, v0
	v_mov_b32_e32 v91, v0
	v_mov_b32_e32 v92, v0
	v_mov_b32_e32 v93, v0
	v_mov_b32_e32 v94, v0
	v_mov_b32_e32 v95, v0
	v_mov_b32_e32 v96, v0
	v_mov_b32_e32 v97, v0
	v_mov_b32_e32 v98, v0
	v_mov_b32_e32 v99, v0
	v_mov_b32_e32 v100, v0
	v_mov_b32_e32 v101, v0
	v_mov_b32_e32 v102, v0
	v_mov_b32_e32 v103, v0
	v_mov_b32_e32 v104, v0
	v_mov_b32_e32 v105, v0
	v_mov_b32_e32 v106, v0
	v_mov_b32_e32 v107, v0
	v_mov_b32_e32 v108, v0
	v_mov_b32_e32 v109, v0
	v_mov_b32_e32 v110, v0
	v_mov_b32_e32 v111, v0
	v_mov_b32_e32 v112, v0
	v_mov_b32_e32 v113, v0
	v_mov_b32_e32 v114, v0
	v_mov_b32_e32 v115, v0
	v_mov_b32_e32 v116, v0
	v_mov_b32_e32 v117, v0
	v_mov_b32_e32 v118, v0
	v_mov_b32_e32 v119, v0
	v_mov_b32_e32 v120, v0
	v_mov_b32_e32 v121, v0
	v_mov_b32_e32 v122, v0
	v_mov_b32_e32 v123, v0
	v_mov_b32_e32 v124, v0
	v_mov_b32_e32 v125, v0
	v_mov_b32_e32 v126, v0
	v_mov_b32_e32 v127, v0
	v_readfirstlane_b32 s56, v166
	v_readfirstlane_b32 s57, v167
	v_readfirstlane_b32 s58, v168
	v_readfirstlane_b32 s59, v169
	v_readfirstlane_b32 s32, v164
	s_nop 3
	s_sub_u32 s56, s56, s32
	s_subb_u32 s57, s57, 0
	s_add_u32 s56, s56, s6
	s_addc_u32 s57, s57, s7
	s_sub_u32 s58, s58, s32
	s_subb_u32 s59, s59, 0
	s_add_u32 s58, s58, s6
	s_addc_u32 s59, s59, s7
	v_add_u32_e32 v240, 0x80, v164
	v_add_u32_e32 v241, 0x20080, v164
	v_add_u32_e32 v242, 0x40080, v164
	v_add_u32_e32 v243, 0x60080, v164
.LBB0_743:
	s_add_i32 s8, s0, 0x10000
	s_and_b32 s9, s8, 0x10000
	s_add_i32 s9, s97, s9
	s_mov_b32 m0, s9
	s_nop 0
	global_load_lds_dwordx4 v240, s[56:57]
	s_add_i32 m0, s9, 0x8000
	s_nop 0
	global_load_lds_dwordx4 v240, s[58:59]
	s_add_i32 m0, s9, 0x2000
	s_nop 0
	global_load_lds_dwordx4 v241, s[56:57]
	s_add_i32 m0, s9, 0xa000
	s_nop 0
	global_load_lds_dwordx4 v241, s[58:59]
	s_add_i32 m0, s9, 0x4000
	s_nop 0
	global_load_lds_dwordx4 v242, s[56:57]
	s_add_i32 m0, s9, 0xc000
	s_nop 0
	global_load_lds_dwordx4 v242, s[58:59]
	s_add_i32 m0, s9, 0x6000
	s_nop 0
	global_load_lds_dwordx4 v243, s[56:57]
	s_add_i32 m0, s9, 0xe000
	s_and_b32 s0, s0, 0x10000
	s_nop 0
	global_load_lds_dwordx4 v243, s[58:59]
	s_add_u32 s56, s56, 0x80
	s_addc_u32 s57, s57, 0
	s_add_u32 s58, s58, 0x80
	s_addc_u32 s59, s59, 0
	s_add_i32 s0, s0, 16
	v_add3_u32 v132, s0, v181, v182
	v_add3_u32 v165, s0, v183, v182
	v_add_u32_e32 v191, v165, v176
	v_add_u32_e32 v200, v132, v176
	ds_read_b128 v[128:131], v191 offset:32768
	ds_read_b128 v[170:173], v200
	ds_read_b128 v[192:195], v191 offset:36864
	ds_read_b128 v[196:199], v200 offset:4096
	ds_read_b128 v[204:207], v200 offset:8192
	ds_read_b128 v[208:211], v200 offset:12288
	s_waitcnt lgkmcnt(0)
	v_mfma_f32_32x32x16_bf16 v[112:127], v[128:131], v[170:173], v[112:127]
	v_add_u32_e32 v174, v165, v177
	v_add_u32_e32 v175, v132, v177
	s_add_u32 s6, s6, 0x80
	s_addc_u32 s7, s7, 0
	s_cmpk_eq_i32 s6, 0x780
	s_mov_b32 s0, s8
	v_mfma_f32_32x32x16_bf16 v[96:111], v[128:131], v[196:199], v[96:111]
	v_mfma_f32_32x32x16_bf16 v[80:95], v[128:131], v[204:207], v[80:95]
	v_mfma_f32_32x32x16_bf16 v[64:79], v[128:131], v[208:211], v[64:79]
	v_mfma_f32_32x32x16_bf16 v[48:63], v[192:195], v[170:173], v[48:63]
	v_mfma_f32_32x32x16_bf16 v[32:47], v[192:195], v[196:199], v[32:47]
	v_mfma_f32_32x32x16_bf16 v[16:31], v[192:195], v[204:207], v[16:31]
	v_mfma_f32_32x32x16_bf16 v[0:15], v[192:195], v[208:211], v[0:15]
	ds_read_b128 v[128:131], v174 offset:32768
	ds_read_b128 v[170:173], v175
	ds_read_b128 v[192:195], v174 offset:36864
	ds_read_b128 v[196:199], v175 offset:4096
	ds_read_b128 v[204:207], v175 offset:8192
	ds_read_b128 v[208:211], v175 offset:12288
	v_add_u32_e32 v174, v165, v178
	v_add_u32_e32 v175, v132, v178
	v_add_u32_e32 v165, v165, v179
	v_add_u32_e32 v132, v132, v179
	s_waitcnt lgkmcnt(0)
; #define MFMA(a, b, c) __builtin_amdgcn_mfma_f32_32x32x16_bf16((a), (b), (c), 0, 0, 0)
; #define G_BARRIER() { asm volatile("s_waitcnt vmcnt(0) lgkmcnt(0)" ::: "memory"); __builtin_amdgcn_s_barrier(); asm volatile("" ::: "memory"); }
;     ...
; #pragma unroll
;             for (int ks = 0; ks < 4; ++ks) {
;                 bf16x8 wfr[2], afr[TB];
; #pragma unroll
;                 for (int fb = 0; fb < 2; ++fb) wfr[fb] = *(const bf16x8*)(sw + fb * 4096 + koff[ks]);
; #pragma unroll
;                 for (int tb = 0; tb < TB; ++tb) afr[tb] = *(const bf16x8*)(sa + tb * 4096 + koff[ks]);
; #pragma unroll
;                 for (int fb = 0; fb < 2; ++fb)
; #pragma unroll
;                     for (int tb = 0; tb < TB; ++tb) acc[fb][tb] = MFMA(wfr[fb], afr[tb], acc[fb][tb]);
;             }
;             G_BARRIER();
	v_mfma_f32_32x32x16_bf16 v[112:127], v[128:131], v[170:173], v[112:127]
	v_mfma_f32_32x32x16_bf16 v[96:111], v[128:131], v[196:199], v[96:111]
	v_mfma_f32_32x32x16_bf16 v[80:95], v[128:131], v[204:207], v[80:95]
	v_mfma_f32_32x32x16_bf16 v[64:79], v[128:131], v[208:211], v[64:79]
	v_mfma_f32_32x32x16_bf16 v[48:63], v[192:195], v[170:173], v[48:63]
	v_mfma_f32_32x32x16_bf16 v[32:47], v[192:195], v[196:199], v[32:47]
	v_mfma_f32_32x32x16_bf16 v[16:31], v[192:195], v[204:207], v[16:31]
	v_mfma_f32_32x32x16_bf16 v[0:15], v[192:195], v[208:211], v[0:15]
	ds_read_b128 v[128:131], v174 offset:32768
	ds_read_b128 v[170:173], v175
	ds_read_b128 v[192:195], v174 offset:36864
	ds_read_b128 v[196:199], v175 offset:4096
	ds_read_b128 v[204:207], v175 offset:8192
	ds_read_b128 v[208:211], v175 offset:12288
	s_waitcnt lgkmcnt(0)
	v_mfma_f32_32x32x16_bf16 v[112:127], v[128:131], v[170:173], v[112:127]
	v_mfma_f32_32x32x16_bf16 v[96:111], v[128:131], v[196:199], v[96:111]
	v_mfma_f32_32x32x16_bf16 v[80:95], v[128:131], v[204:207], v[80:95]
	v_mfma_f32_32x32x16_bf16 v[64:79], v[128:131], v[208:211], v[64:79]
	v_mfma_f32_32x32x16_bf16 v[48:63], v[192:195], v[170:173], v[48:63]
	v_mfma_f32_32x32x16_bf16 v[32:47], v[192:195], v[196:199], v[32:47]
	v_mfma_f32_32x32x16_bf16 v[16:31], v[192:195], v[204:207], v[16:31]
	v_mfma_f32_32x32x16_bf16 v[0:15], v[192:195], v[208:211], v[0:15]
	ds_read_b128 v[128:131], v165 offset:32768
	ds_read_b128 v[170:173], v132
	ds_read_b128 v[192:195], v165 offset:36864
	ds_read_b128 v[196:199], v132 offset:4096
	ds_read_b128 v[204:207], v132 offset:8192
	ds_read_b128 v[208:211], v132 offset:12288
	s_waitcnt vmcnt(0) lgkmcnt(0)
	s_barrier
	s_waitcnt lgkmcnt(0)
	v_mfma_f32_32x32x16_bf16 v[112:127], v[128:131], v[170:173], v[112:127]
	v_mfma_f32_32x32x16_bf16 v[96:111], v[128:131], v[196:199], v[96:111]
	v_mfma_f32_32x32x16_bf16 v[80:95], v[128:131], v[204:207], v[80:95]
	v_mfma_f32_32x32x16_bf16 v[64:79], v[128:131], v[208:211], v[64:79]
	v_mfma_f32_32x32x16_bf16 v[48:63], v[192:195], v[170:173], v[48:63]
	v_mfma_f32_32x32x16_bf16 v[32:47], v[192:195], v[196:199], v[32:47]
	v_mfma_f32_32x32x16_bf16 v[16:31], v[192:195], v[204:207], v[16:31]
	v_mfma_f32_32x32x16_bf16 v[0:15], v[192:195], v[208:211], v[0:15]
	s_cbranch_scc0 .LBB0_743
; #define GAS __attribute__((address_space(1)))
; #define MFMA(a, b, c) __builtin_amdgcn_mfma_f32_32x32x16_bf16((a), (b), (c), 0, 0, 0)
; #define G_BARRIER() { asm volatile("s_waitcnt vmcnt(0) lgkmcnt(0)" ::: "memory"); __builtin_amdgcn_s_barrier(); asm volatile("" ::: "memory"); }
;     ...
;         for (int kt = 0; kt < nk; ++kt) {
;             if (kt + 1 < nk) { G_DMA(kt + 1, (kt + 1) & 1); }
;             const unsigned char* sa = lds + (kt & 1) * 65536 + (wt * 32 * TB + r) * 128;
;             const unsigned char* sw = lds + (kt & 1) * 65536 + 32768 + (wf * 64 + r) * 128;
; #pragma unroll
;             for (int ks = 0; ks < 4; ++ks) {
;                 bf16x8 wfr[2], afr[TB];
; #pragma unroll
;                 for (int fb = 0; fb < 2; ++fb) wfr[fb] = *(const bf16x8*)(sw + fb * 4096 + koff[ks]);
; #pragma unroll
;                 for (int tb = 0; tb < TB; ++tb) afr[tb] = *(const bf16x8*)(sa + tb * 4096 + koff[ks]);
; #pragma unroll
;                 for (int fb = 0; fb < 2; ++fb)
; #pragma unroll
;                     for (int tb = 0; tb < TB; ++tb) acc[fb][tb] = MFMA(wfr[fb], afr[tb], acc[fb][tb]);
;             }
;             G_BARRIER();
;         }
;         const int un = u + nslots;
;         if (un < nloc) {
;             Ag = (const GAS bf16_t*)(A + (size_t)(xcd + nx * (un / Ntiles)) * RM * K) + dsrc; Wg = (const GAS bf16_t*)(Wt + (size_t)(un % Ntiles) * 256 * K) + dsrc;
;             G_DMA(0, 0);
;         }
	v_add_u32_e32 v132, v187, v176
	ds_read_b128 v[128:131], v132
	v_add_u32_e32 v165, v186, v176
	ds_read_b128 v[170:173], v165
	ds_read_b128 v[192:195], v165 offset:4096
	ds_read_b128 v[196:199], v165 offset:8192
	ds_read_b128 v[204:207], v165 offset:12288
	v_add_u32_e32 v165, v186, v177
	s_add_i32 s0, s1, s71
	s_cmp_ge_i32 s0, s72
	s_waitcnt lgkmcnt(0)
	v_mfma_f32_32x32x16_bf16 v[112:127], v[128:131], v[170:173], v[112:127]
	s_cselect_b64 s[60:61], -1, 0
	s_cmp_lt_i32 s0, s72
	v_mfma_f32_32x32x16_bf16 v[96:111], v[128:131], v[192:195], v[96:111]
	v_mfma_f32_32x32x16_bf16 v[80:95], v[128:131], v[196:199], v[80:95]
	v_mfma_f32_32x32x16_bf16 v[64:79], v[128:131], v[204:207], v[64:79]
	ds_read_b128 v[128:131], v132 offset:4096
	v_add_u32_e32 v132, v187, v177
	s_waitcnt lgkmcnt(0)
	v_mfma_f32_32x32x16_bf16 v[48:63], v[128:131], v[170:173], v[48:63]
	ds_read_b128 v[170:173], v165
	v_mfma_f32_32x32x16_bf16 v[32:47], v[128:131], v[192:195], v[32:47]
	ds_read_b128 v[192:195], v165 offset:4096
	v_mfma_f32_32x32x16_bf16 v[16:31], v[128:131], v[196:199], v[16:31]
	ds_read_b128 v[196:199], v165 offset:8192
	v_mfma_f32_32x32x16_bf16 v[0:15], v[128:131], v[204:207], v[0:15]
	ds_read_b128 v[128:131], v132
	ds_read_b128 v[204:207], v165 offset:12288
	v_add_u32_e32 v165, v186, v178
	s_waitcnt lgkmcnt(0)
	v_mfma_f32_32x32x16_bf16 v[112:127], v[128:131], v[170:173], v[112:127]
	v_mfma_f32_32x32x16_bf16 v[96:111], v[128:131], v[192:195], v[96:111]
	v_mfma_f32_32x32x16_bf16 v[80:95], v[128:131], v[196:199], v[80:95]
	v_mfma_f32_32x32x16_bf16 v[64:79], v[128:131], v[204:207], v[64:79]
	ds_read_b128 v[128:131], v132 offset:4096
	v_add_u32_e32 v132, v187, v178
	s_waitcnt lgkmcnt(0)
	v_mfma_f32_32x32x16_bf16 v[48:63], v[128:131], v[170:173], v[48:63]
	ds_read_b128 v[170:173], v165
	v_mfma_f32_32x32x16_bf16 v[32:47], v[128:131], v[192:195], v[32:47]
	ds_read_b128 v[192:195], v165 offset:4096
	v_mfma_f32_32x32x16_bf16 v[16:31], v[128:131], v[196:199], v[16:31]
	ds_read_b128 v[196:199], v165 offset:8192
	v_mfma_f32_32x32x16_bf16 v[0:15], v[128:131], v[204:207], v[0:15]
	ds_read_b128 v[128:131], v132
	ds_read_b128 v[204:207], v165 offset:12288
	v_add_u32_e32 v165, v186, v179
	s_waitcnt lgkmcnt(0)
	v_mfma_f32_32x32x16_bf16 v[112:127], v[128:131], v[170:173], v[112:127]
	v_mfma_f32_32x32x16_bf16 v[96:111], v[128:131], v[192:195], v[96:111]
	v_mfma_f32_32x32x16_bf16 v[80:95], v[128:131], v[196:199], v[80:95]
	v_mfma_f32_32x32x16_bf16 v[64:79], v[128:131], v[204:207], v[64:79]
	ds_read_b128 v[128:131], v132 offset:4096
	v_add_u32_e32 v132, v187, v179
	s_waitcnt lgkmcnt(0)
	v_mfma_f32_32x32x16_bf16 v[48:63], v[128:131], v[170:173], v[48:63]
	ds_read_b128 v[170:173], v165
	v_mfma_f32_32x32x16_bf16 v[32:47], v[128:131], v[192:195], v[32:47]
	ds_read_b128 v[192:195], v165 offset:4096
	v_mfma_f32_32x32x16_bf16 v[16:31], v[128:131], v[196:199], v[16:31]
	ds_read_b128 v[196:199], v165 offset:8192
	v_mfma_f32_32x32x16_bf16 v[0:15], v[128:131], v[204:207], v[0:15]
	ds_read_b128 v[128:131], v132
	ds_read_b128 v[204:207], v165 offset:12288
	s_waitcnt lgkmcnt(0)
	v_mfma_f32_32x32x16_bf16 v[112:127], v[128:131], v[170:173], v[112:127]
	v_mfma_f32_32x32x16_bf16 v[96:111], v[128:131], v[192:195], v[96:111]
	v_mfma_f32_32x32x16_bf16 v[80:95], v[128:131], v[196:199], v[80:95]
	v_mfma_f32_32x32x16_bf16 v[64:79], v[128:131], v[204:207], v[64:79]
	ds_read_b128 v[128:131], v132 offset:4096
	s_waitcnt vmcnt(0) lgkmcnt(0)
	s_barrier
	s_waitcnt lgkmcnt(0)
	v_mfma_f32_32x32x16_bf16 v[48:63], v[128:131], v[170:173], v[48:63]
	v_mfma_f32_32x32x16_bf16 v[32:47], v[128:131], v[192:195], v[32:47]
	v_mfma_f32_32x32x16_bf16 v[16:31], v[128:131], v[196:199], v[16:31]
	v_mfma_f32_32x32x16_bf16 v[0:15], v[128:131], v[204:207], v[0:15]
	s_cbranch_scc0 .LBB0_746
	s_mul_hi_i32 s6, s0, 0x2aaaaaab
	s_lshr_b32 s7, s6, 31
	s_add_i32 s8, s6, s7
	s_lshl_b32 s6, s8, s67
	s_add_i32 s6, s6, s70
	s_ashr_i32 s7, s6, 31
	s_lshl_b64 s[6:7], s[6:7], 19
	s_add_u32 s6, s38, s6
	s_mul_i32 s8, s8, 6
	s_addc_u32 s7, s39, s7
	s_sub_i32 s8, s0, s8
	s_ashr_i32 s9, s8, 31
	s_lshl_b64 s[8:9], s[8:9], 19
	s_mov_b32 m0, s97
	v_mov_b32_e32 v165, v133
	s_add_u32 s8, s40, s8
	v_lshl_add_u64 v[166:167], s[6:7], 0, v[164:165]
	s_addc_u32 s9, s41, s9
	global_load_lds_dwordx4 v164, s[6:7]
	s_add_i32 m0, s97, 0x8000
	v_lshl_add_u64 v[168:169], s[8:9], 0, v[164:165]
	global_load_lds_dwordx4 v164, s[8:9]
	v_lshl_add_u64 v[128:129], v[166:167], 0, s[44:45]
	s_add_i32 m0, s97, 0x2000
	s_nop 0
	global_load_lds_dwordx4 v[128:129], off
	v_lshl_add_u64 v[128:129], v[168:169], 0, s[44:45]
	s_add_i32 m0, s97, 0xa000
	s_nop 0
	global_load_lds_dwordx4 v[128:129], off
	v_lshl_add_u64 v[128:129], v[166:167], 0, s[46:47]
	s_add_i32 m0, s97, 0x4000
	s_nop 0
	global_load_lds_dwordx4 v[128:129], off
	v_lshl_add_u64 v[128:129], v[168:169], 0, s[46:47]
	s_add_i32 m0, s97, 0xc000
	s_nop 0
	global_load_lds_dwordx4 v[128:129], off
	v_lshl_add_u64 v[128:129], v[166:167], 0, s[48:49]
	s_add_i32 m0, s97, 0x6000
	s_nop 0
	global_load_lds_dwordx4 v[128:129], off
	v_lshl_add_u64 v[128:129], v[168:169], 0, s[48:49]
	s_add_i32 m0, s97, 0xe000
	s_nop 0
	global_load_lds_dwordx4 v[128:129], off

; #define MFMA(a, b, c) __builtin_amdgcn_mfma_f32_32x32x16_bf16((a), (b), (c), 0, 0, 0)
; #define G_BARRIER() { asm volatile("s_waitcnt vmcnt(0) lgkmcnt(0)" ::: "memory"); __builtin_amdgcn_s_barrier(); asm volatile("" ::: "memory"); }
;     ...
; #pragma unroll
;         for (int a = 0; a < 2; ++a)
; #pragma unroll
;             for (int b = 0; b < TB; ++b)
; #pragma unroll
;                 for (int i = 0; i < 16; ++i) acc[a][b][i] = 0.f;
;         G_BARRIER();
;         for (int kt = 0; kt < nk; ++kt) {
;             if (kt + 1 < nk) { G_DMA(kt + 1, (kt + 1) & 1); }
;             const unsigned char* sa = lds + (kt & 1) * 65536 + (wt * 32 * TB + r) * 128;
;             const unsigned char* sw = lds + (kt & 1) * 65536 + 32768 + (wf * 64 + r) * 128;
; #pragma unroll
;             for (int ks = 0; ks < 4; ++ks) {
;                 bf16x8 wfr[2], afr[TB];
; #pragma unroll
;                 for (int fb = 0; fb < 2; ++fb) wfr[fb] = *(const bf16x8*)(sw + fb * 4096 + koff[ks]);
; #pragma unroll
;                 for (int tb = 0; tb < TB; ++tb) afr[tb] = *(const bf16x8*)(sa + tb * 4096 + koff[ks]);
; #pragma unroll
;                 for (int fb = 0; fb < 2; ++fb)
; #pragma unroll
;                     for (int tb = 0; tb < TB; ++tb) acc[fb][tb] = MFMA(wfr[fb], afr[tb], acc[fb][tb]);
;             }
;             G_BARRIER();
.LBB0_1174:
	s_waitcnt vmcnt(0) lgkmcnt(0)
	s_barrier
	v_mov_b32_e32 v0, 0
	s_mov_b32 s54, s53
	s_mov_b32 s53, 0
	s_mov_b64 s[42:43], 0
	v_mov_b32_e32 v1, v0
	v_mov_b32_e32 v2, v0
	v_mov_b32_e32 v3, v0
	v_mov_b32_e32 v4, v0
	v_mov_b32_e32 v5, v0
	v_mov_b32_e32 v6, v0
	v_mov_b32_e32 v7, v0
	v_mov_b32_e32 v8, v0
	v_mov_b32_e32 v9, v0
	v_mov_b32_e32 v10, v0
	v_mov_b32_e32 v11, v0
	v_mov_b32_e32 v12, v0
	v_mov_b32_e32 v13, v0
	v_mov_b32_e32 v14, v0
	v_mov_b32_e32 v15, v0
	v_mov_b32_e32 v16, v0
	v_mov_b32_e32 v17, v0
	v_mov_b32_e32 v18, v0
	v_mov_b32_e32 v19, v0
	v_mov_b32_e32 v20, v0
	v_mov_b32_e32 v21, v0
	v_mov_b32_e32 v22, v0
	v_mov_b32_e32 v23, v0
	v_mov_b32_e32 v24, v0
	v_mov_b32_e32 v25, v0
	v_mov_b32_e32 v26, v0
	v_mov_b32_e32 v27, v0
	v_mov_b32_e32 v28, v0
	v_mov_b32_e32 v29, v0
	v_mov_b32_e32 v30, v0
	v_mov_b32_e32 v31, v0
	v_mov_b32_e32 v32, v0
	v_mov_b32_e32 v33, v0
	v_mov_b32_e32 v34, v0
	v_mov_b32_e32 v35, v0
	v_mov_b32_e32 v36, v0
	v_mov_b32_e32 v37, v0
	v_mov_b32_e32 v38, v0
	v_mov_b32_e32 v39, v0
	v_mov_b32_e32 v40, v0
	v_mov_b32_e32 v41, v0
	v_mov_b32_e32 v42, v0
	v_mov_b32_e32 v43, v0
	v_mov_b32_e32 v44, v0
	v_mov_b32_e32 v45, v0
	v_mov_b32_e32 v46, v0
	v_mov_b32_e32 v47, v0
	v_mov_b32_e32 v48, v0
	v_mov_b32_e32 v49, v0
	v_mov_b32_e32 v50, v0
	v_mov_b32_e32 v51, v0
	v_mov_b32_e32 v52, v0
	v_mov_b32_e32 v53, v0
	v_mov_b32_e32 v54, v0
	v_mov_b32_e32 v55, v0
	v_mov_b32_e32 v56, v0
	v_mov_b32_e32 v57, v0
	v_mov_b32_e32 v58, v0
	v_mov_b32_e32 v59, v0
	v_mov_b32_e32 v60, v0
	v_mov_b32_e32 v61, v0
	v_mov_b32_e32 v62, v0
	v_mov_b32_e32 v63, v0
	v_mov_b32_e32 v64, v0
	v_mov_b32_e32 v65, v0
	v_mov_b32_e32 v66, v0
	v_mov_b32_e32 v67, v0
	v_mov_b32_e32 v68, v0
	v_mov_b32_e32 v69, v0
	v_mov_b32_e32 v70, v0
	v_mov_b32_e32 v71, v0
	v_mov_b32_e32 v72, v0
	v_mov_b32_e32 v73, v0
	v_mov_b32_e32 v74, v0
	v_mov_b32_e32 v75, v0
	v_mov_b32_e32 v76, v0
	v_mov_b32_e32 v77, v0
	v_mov_b32_e32 v78, v0
	v_mov_b32_e32 v79, v0
	v_mov_b32_e32 v80, v0
	v_mov_b32_e32 v81, v0
	v_mov_b32_e32 v82, v0
	v_mov_b32_e32 v83, v0
	v_mov_b32_e32 v84, v0
	v_mov_b32_e32 v85, v0
	v_mov_b32_e32 v86, v0
	v_mov_b32_e32 v87, v0
	v_mov_b32_e32 v88, v0
	v_mov_b32_e32 v89, v0
	v_mov_b32_e32 v90, v0
	v_mov_b32_e32 v91, v0
	v_mov_b32_e32 v92, v0
	v_mov_b32_e32 v93, v0
	v_mov_b32_e32 v94, v0
	v_mov_b32_e32 v95, v0
	v_mov_b32_e32 v96, v0
	v_mov_b32_e32 v97, v0
	v_mov_b32_e32 v98, v0
	v_mov_b32_e32 v99, v0
	v_mov_b32_e32 v100, v0
	v_mov_b32_e32 v101, v0
	v_mov_b32_e32 v102, v0
	v_mov_b32_e32 v103, v0
	v_mov_b32_e32 v104, v0
	v_mov_b32_e32 v105, v0
	v_mov_b32_e32 v106, v0
	v_mov_b32_e32 v107, v0
	v_mov_b32_e32 v108, v0
	v_mov_b32_e32 v109, v0
	v_mov_b32_e32 v110, v0
	v_mov_b32_e32 v111, v0
	v_mov_b32_e32 v112, v0
	v_mov_b32_e32 v113, v0
	v_mov_b32_e32 v114, v0
	v_mov_b32_e32 v115, v0
	v_mov_b32_e32 v116, v0
	v_mov_b32_e32 v117, v0
	v_mov_b32_e32 v118, v0
	v_mov_b32_e32 v119, v0
	v_mov_b32_e32 v120, v0
	v_mov_b32_e32 v121, v0
	v_mov_b32_e32 v122, v0
	v_mov_b32_e32 v123, v0
	v_mov_b32_e32 v124, v0
	v_mov_b32_e32 v125, v0
	v_mov_b32_e32 v126, v0
	v_mov_b32_e32 v127, v0
	v_readfirstlane_b32 s60, v150
	v_readfirstlane_b32 s61, v151
	v_readfirstlane_b32 s62, v152
	v_readfirstlane_b32 s63, v153
	v_readfirstlane_b32 s32, v148
	s_nop 3
	s_sub_u32 s60, s60, s32
	s_subb_u32 s61, s61, 0
	s_add_u32 s60, s60, s42
	s_addc_u32 s61, s61, s43
	s_sub_u32 s62, s62, s32
	s_subb_u32 s63, s63, 0
	s_add_u32 s62, s62, s42
	s_addc_u32 s63, s63, s43
	v_add_u32_e32 v240, 0x80, v148
	v_add_u32_e32 v241, 0x20080, v148
	v_add_u32_e32 v242, 0x40080, v148
	v_add_u32_e32 v243, 0x60080, v148
.LBB0_1175:
	s_add_i32 s55, s53, 0x10000
	s_and_b32 s56, s55, 0x10000
	s_add_i32 s56, s45, s56
	s_mov_b32 m0, s56
	s_nop 0
	global_load_lds_dwordx4 v240, s[60:61]
	s_add_i32 m0, s56, 0x8000
	s_nop 0
	global_load_lds_dwordx4 v240, s[62:63]
	s_add_i32 m0, s56, 0x2000
	s_nop 0
	global_load_lds_dwordx4 v241, s[60:61]
	s_add_i32 m0, s56, 0xa000
	s_nop 0
	global_load_lds_dwordx4 v241, s[62:63]
	s_add_i32 m0, s56, 0x4000
	s_nop 0
	global_load_lds_dwordx4 v242, s[60:61]
	s_add_i32 m0, s56, 0xc000
	s_nop 0
	global_load_lds_dwordx4 v242, s[62:63]
	s_add_i32 m0, s56, 0x6000
	s_nop 0
	global_load_lds_dwordx4 v243, s[60:61]
	s_add_i32 m0, s56, 0xe000
	s_and_b32 s53, s53, 0x10000
	s_nop 0
	global_load_lds_dwordx4 v243, s[62:63]
	s_add_u32 s60, s60, 0x80
	s_addc_u32 s61, s61, 0
	s_add_u32 s62, s62, 0x80
	s_addc_u32 s63, s63, 0
	s_add_i32 s53, s53, 16
	v_add3_u32 v149, s53, v184, v185
	v_add3_u32 v192, s53, v186, v185
	v_add_u32_e32 v170, v192, v179
	v_add_u32_e32 v174, v149, v179
	ds_read_b128 v[154:157], v170 offset:32768
	ds_read_b128 v[158:161], v174
	ds_read_b128 v[162:165], v170 offset:36864
	ds_read_b128 v[166:169], v174 offset:4096
	ds_read_b128 v[170:173], v174 offset:8192
	ds_read_b128 v[174:177], v174 offset:12288
	s_waitcnt lgkmcnt(0)
	v_mfma_f32_32x32x16_bf16 v[112:127], v[154:157], v[158:161], v[112:127]
	v_add_u32_e32 v193, v149, v180
	s_add_u32 s42, s42, 0x80
	s_addc_u32 s43, s43, 0
	s_cmpk_eq_i32 s42, 0x780
	s_mov_b32 s53, s55
	v_mfma_f32_32x32x16_bf16 v[96:111], v[154:157], v[166:169], v[96:111]
	v_mfma_f32_32x32x16_bf16 v[80:95], v[154:157], v[170:173], v[80:95]
	v_mfma_f32_32x32x16_bf16 v[64:79], v[154:157], v[174:177], v[64:79]
	v_mfma_f32_32x32x16_bf16 v[48:63], v[162:165], v[158:161], v[48:63]
	v_mfma_f32_32x32x16_bf16 v[32:47], v[162:165], v[166:169], v[32:47]
	v_add_u32_e32 v166, v192, v180
	v_mfma_f32_32x32x16_bf16 v[16:31], v[162:165], v[170:173], v[16:31]
	v_mfma_f32_32x32x16_bf16 v[0:15], v[162:165], v[174:177], v[0:15]
	ds_read_b128 v[154:157], v166 offset:32768
	ds_read_b128 v[158:161], v193
	ds_read_b128 v[162:165], v166 offset:36864
	ds_read_b128 v[166:169], v193 offset:4096
	ds_read_b128 v[170:173], v193 offset:8192
	ds_read_b128 v[174:177], v193 offset:12288
	v_add_u32_e32 v193, v149, v181
	v_add_u32_e32 v149, v149, v182
	s_waitcnt lgkmcnt(0)
; #define MFMA(a, b, c) __builtin_amdgcn_mfma_f32_32x32x16_bf16((a), (b), (c), 0, 0, 0)
; #define G_BARRIER() { asm volatile("s_waitcnt vmcnt(0) lgkmcnt(0)" ::: "memory"); __builtin_amdgcn_s_barrier(); asm volatile("" ::: "memory"); }
;     ...
; #pragma unroll
;             for (int ks = 0; ks < 4; ++ks) {
;                 bf16x8 wfr[2], afr[TB];
; #pragma unroll
;                 for (int fb = 0; fb < 2; ++fb) wfr[fb] = *(const bf16x8*)(sw + fb * 4096 + koff[ks]);
; #pragma unroll
;                 for (int tb = 0; tb < TB; ++tb) afr[tb] = *(const bf16x8*)(sa + tb * 4096 + koff[ks]);
; #pragma unroll
;                 for (int fb = 0; fb < 2; ++fb)
; #pragma unroll
;                     for (int tb = 0; tb < TB; ++tb) acc[fb][tb] = MFMA(wfr[fb], afr[tb], acc[fb][tb]);
;             }
;             G_BARRIER();
	v_mfma_f32_32x32x16_bf16 v[112:127], v[154:157], v[158:161], v[112:127]
	v_mfma_f32_32x32x16_bf16 v[96:111], v[154:157], v[166:169], v[96:111]
	v_mfma_f32_32x32x16_bf16 v[80:95], v[154:157], v[170:173], v[80:95]
	v_mfma_f32_32x32x16_bf16 v[64:79], v[154:157], v[174:177], v[64:79]
	v_mfma_f32_32x32x16_bf16 v[48:63], v[162:165], v[158:161], v[48:63]
	v_mfma_f32_32x32x16_bf16 v[32:47], v[162:165], v[166:169], v[32:47]
	v_add_u32_e32 v166, v192, v181
	v_mfma_f32_32x32x16_bf16 v[16:31], v[162:165], v[170:173], v[16:31]
	v_mfma_f32_32x32x16_bf16 v[0:15], v[162:165], v[174:177], v[0:15]
	ds_read_b128 v[154:157], v166 offset:32768
	ds_read_b128 v[158:161], v193
	ds_read_b128 v[162:165], v166 offset:36864
	ds_read_b128 v[166:169], v193 offset:4096
	ds_read_b128 v[170:173], v193 offset:8192
	ds_read_b128 v[174:177], v193 offset:12288
	s_waitcnt lgkmcnt(0)
	v_mfma_f32_32x32x16_bf16 v[112:127], v[154:157], v[158:161], v[112:127]
	v_mfma_f32_32x32x16_bf16 v[96:111], v[154:157], v[166:169], v[96:111]
	v_mfma_f32_32x32x16_bf16 v[80:95], v[154:157], v[170:173], v[80:95]
	v_mfma_f32_32x32x16_bf16 v[64:79], v[154:157], v[174:177], v[64:79]
	v_mfma_f32_32x32x16_bf16 v[48:63], v[162:165], v[158:161], v[48:63]
	v_mfma_f32_32x32x16_bf16 v[32:47], v[162:165], v[166:169], v[32:47]
	v_add_u32_e32 v166, v192, v182
	v_mfma_f32_32x32x16_bf16 v[16:31], v[162:165], v[170:173], v[16:31]
	v_mfma_f32_32x32x16_bf16 v[0:15], v[162:165], v[174:177], v[0:15]
	ds_read_b128 v[154:157], v166 offset:32768
	ds_read_b128 v[158:161], v149
	ds_read_b128 v[162:165], v166 offset:36864
	ds_read_b128 v[166:169], v149 offset:4096
	ds_read_b128 v[170:173], v149 offset:8192
	ds_read_b128 v[174:177], v149 offset:12288
	s_waitcnt vmcnt(0) lgkmcnt(0)
	s_barrier
	s_waitcnt lgkmcnt(0)
	v_mfma_f32_32x32x16_bf16 v[112:127], v[154:157], v[158:161], v[112:127]
	v_mfma_f32_32x32x16_bf16 v[96:111], v[154:157], v[166:169], v[96:111]
	v_mfma_f32_32x32x16_bf16 v[80:95], v[154:157], v[170:173], v[80:95]
	v_mfma_f32_32x32x16_bf16 v[64:79], v[154:157], v[174:177], v[64:79]
	v_mfma_f32_32x32x16_bf16 v[48:63], v[162:165], v[158:161], v[48:63]
	v_mfma_f32_32x32x16_bf16 v[32:47], v[162:165], v[166:169], v[32:47]
	v_mfma_f32_32x32x16_bf16 v[16:31], v[162:165], v[170:173], v[16:31]
	v_mfma_f32_32x32x16_bf16 v[0:15], v[162:165], v[174:177], v[0:15]
	s_cbranch_scc0 .LBB0_1175
; #define GAS __attribute__((address_space(1)))
; #define MFMA(a, b, c) __builtin_amdgcn_mfma_f32_32x32x16_bf16((a), (b), (c), 0, 0, 0)
; #define G_BARRIER() { asm volatile("s_waitcnt vmcnt(0) lgkmcnt(0)" ::: "memory"); __builtin_amdgcn_s_barrier(); asm volatile("" ::: "memory"); }
;     ...
;         for (int kt = 0; kt < nk; ++kt) {
;             if (kt + 1 < nk) { G_DMA(kt + 1, (kt + 1) & 1); }
;             const unsigned char* sa = lds + (kt & 1) * 65536 + (wt * 32 * TB + r) * 128;
;             const unsigned char* sw = lds + (kt & 1) * 65536 + 32768 + (wf * 64 + r) * 128;
; #pragma unroll
;             for (int ks = 0; ks < 4; ++ks) {
;                 bf16x8 wfr[2], afr[TB];
; #pragma unroll
;                 for (int fb = 0; fb < 2; ++fb) wfr[fb] = *(const bf16x8*)(sw + fb * 4096 + koff[ks]);
; #pragma unroll
;                 for (int tb = 0; tb < TB; ++tb) afr[tb] = *(const bf16x8*)(sa + tb * 4096 + koff[ks]);
; #pragma unroll
;                 for (int fb = 0; fb < 2; ++fb)
; #pragma unroll
;                     for (int tb = 0; tb < TB; ++tb) acc[fb][tb] = MFMA(wfr[fb], afr[tb], acc[fb][tb]);
;             }
;             G_BARRIER();
;         }
;         const int un = u + nslots;
;         if (un < nloc) {
;             Ag = (const GAS bf16_t*)(A + (size_t)(xcd + nx * (un / Ntiles)) * RM * K) + dsrc; Wg = (const GAS bf16_t*)(Wt + (size_t)(un % Ntiles) * 256 * K) + dsrc;
;             G_DMA(0, 0);
;         }
	v_add_u32_e32 v149, v190, v179
	ds_read_b128 v[154:157], v149
	v_add_u32_e32 v170, v189, v179
	ds_read_b128 v[158:161], v170
	ds_read_b128 v[162:165], v170 offset:4096
	ds_read_b128 v[166:169], v170 offset:8192
	ds_read_b128 v[170:173], v170 offset:12288
	s_add_i32 s53, s54, s34
	s_cmp_ge_i32 s53, s35
	s_cselect_b64 s[42:43], -1, 0
	s_waitcnt lgkmcnt(0)
	v_mfma_f32_32x32x16_bf16 v[112:127], v[154:157], v[158:161], v[112:127]
	s_cmp_lt_i32 s53, s35
	v_mfma_f32_32x32x16_bf16 v[96:111], v[154:157], v[162:165], v[96:111]
	v_mfma_f32_32x32x16_bf16 v[80:95], v[154:157], v[166:169], v[80:95]
	v_mfma_f32_32x32x16_bf16 v[64:79], v[154:157], v[170:173], v[64:79]
	ds_read_b128 v[154:157], v149 offset:4096
	v_add_u32_e32 v149, v190, v180
	s_waitcnt lgkmcnt(0)
	v_mfma_f32_32x32x16_bf16 v[48:63], v[154:157], v[158:161], v[48:63]
	v_mfma_f32_32x32x16_bf16 v[32:47], v[154:157], v[162:165], v[32:47]
	v_mfma_f32_32x32x16_bf16 v[16:31], v[154:157], v[166:169], v[16:31]
	v_mfma_f32_32x32x16_bf16 v[0:15], v[154:157], v[170:173], v[0:15]
	ds_read_b128 v[154:157], v149
	v_add_u32_e32 v170, v189, v180
	ds_read_b128 v[158:161], v170
	ds_read_b128 v[162:165], v170 offset:4096
	ds_read_b128 v[166:169], v170 offset:8192
	ds_read_b128 v[170:173], v170 offset:12288
	s_waitcnt lgkmcnt(0)
	v_mfma_f32_32x32x16_bf16 v[112:127], v[154:157], v[158:161], v[112:127]
	v_mfma_f32_32x32x16_bf16 v[96:111], v[154:157], v[162:165], v[96:111]
	v_mfma_f32_32x32x16_bf16 v[80:95], v[154:157], v[166:169], v[80:95]
	v_mfma_f32_32x32x16_bf16 v[64:79], v[154:157], v[170:173], v[64:79]
	ds_read_b128 v[154:157], v149 offset:4096
	v_add_u32_e32 v149, v190, v181
	s_waitcnt lgkmcnt(0)
	v_mfma_f32_32x32x16_bf16 v[48:63], v[154:157], v[158:161], v[48:63]
	v_mfma_f32_32x32x16_bf16 v[32:47], v[154:157], v[162:165], v[32:47]
	v_mfma_f32_32x32x16_bf16 v[16:31], v[154:157], v[166:169], v[16:31]
	v_mfma_f32_32x32x16_bf16 v[0:15], v[154:157], v[170:173], v[0:15]
	ds_read_b128 v[154:157], v149
	v_add_u32_e32 v170, v189, v181
	ds_read_b128 v[158:161], v170
	ds_read_b128 v[162:165], v170 offset:4096
	ds_read_b128 v[166:169], v170 offset:8192
	ds_read_b128 v[170:173], v170 offset:12288
	s_waitcnt lgkmcnt(0)
	v_mfma_f32_32x32x16_bf16 v[112:127], v[154:157], v[158:161], v[112:127]
	v_mfma_f32_32x32x16_bf16 v[96:111], v[154:157], v[162:165], v[96:111]
	v_mfma_f32_32x32x16_bf16 v[80:95], v[154:157], v[166:169], v[80:95]
	v_mfma_f32_32x32x16_bf16 v[64:79], v[154:157], v[170:173], v[64:79]
	ds_read_b128 v[154:157], v149 offset:4096
	v_add_u32_e32 v149, v190, v182
	s_waitcnt lgkmcnt(0)
	v_mfma_f32_32x32x16_bf16 v[48:63], v[154:157], v[158:161], v[48:63]
	v_mfma_f32_32x32x16_bf16 v[32:47], v[154:157], v[162:165], v[32:47]
	v_mfma_f32_32x32x16_bf16 v[16:31], v[154:157], v[166:169], v[16:31]
	v_mfma_f32_32x32x16_bf16 v[0:15], v[154:157], v[170:173], v[0:15]
	ds_read_b128 v[154:157], v149
	v_add_u32_e32 v170, v189, v182
	ds_read_b128 v[158:161], v170
	ds_read_b128 v[162:165], v170 offset:4096
	ds_read_b128 v[166:169], v170 offset:8192
	ds_read_b128 v[170:173], v170 offset:12288
	s_waitcnt lgkmcnt(0)
	v_mfma_f32_32x32x16_bf16 v[112:127], v[154:157], v[158:161], v[112:127]
	v_mfma_f32_32x32x16_bf16 v[96:111], v[154:157], v[162:165], v[96:111]
	v_mfma_f32_32x32x16_bf16 v[80:95], v[154:157], v[166:169], v[80:95]
	v_mfma_f32_32x32x16_bf16 v[64:79], v[154:157], v[170:173], v[64:79]
	ds_read_b128 v[154:157], v149 offset:4096
	s_waitcnt vmcnt(0) lgkmcnt(0)
	s_barrier
	s_waitcnt lgkmcnt(0)
	v_mfma_f32_32x32x16_bf16 v[48:63], v[154:157], v[158:161], v[48:63]
	v_mfma_f32_32x32x16_bf16 v[32:47], v[154:157], v[162:165], v[32:47]
	v_mfma_f32_32x32x16_bf16 v[16:31], v[154:157], v[166:169], v[16:31]
	v_mfma_f32_32x32x16_bf16 v[0:15], v[154:157], v[170:173], v[0:15]
	s_cbranch_scc0 .LBB0_1173
	s_ashr_i32 s55, s53, 31
	s_lshr_b32 s55, s55, 30
	s_add_i32 s55, s53, s55
	s_ashr_i32 s56, s55, 2
	s_lshl_b32 s56, s56, s27
	s_add_i32 s56, s56, s33
	s_ashr_i32 s57, s56, 31
	s_lshl_b64 s[56:57], s[56:57], 19
	s_add_u32 s56, s1, s56
	s_addc_u32 s57, s3, s57
	s_and_b32 s55, s55, -4
	s_sub_i32 s58, s53, s55
	s_ashr_i32 s59, s58, 31
	s_lshl_b64 s[58:59], s[58:59], 19
	s_mov_b32 m0, s45
	v_mov_b32_e32 v149, v129
	s_add_u32 s58, s18, s58
	v_lshl_add_u64 v[150:151], s[56:57], 0, v[148:149]
	s_addc_u32 s59, s19, s59
	global_load_lds_dwordx4 v148, s[56:57]
	s_mov_b32 m0, s46
	v_lshl_add_u64 v[152:153], s[58:59], 0, v[148:149]
	global_load_lds_dwordx4 v148, s[58:59]
	v_lshl_add_u64 v[154:155], v[150:151], 0, s[14:15]
	s_mov_b32 m0, s47
	s_nop 0
	global_load_lds_dwordx4 v[154:155], off
	v_lshl_add_u64 v[154:155], v[152:153], 0, s[14:15]
	s_mov_b32 m0, s48
	s_nop 0
	global_load_lds_dwordx4 v[154:155], off
	v_lshl_add_u64 v[154:155], v[150:151], 0, s[16:17]
	s_mov_b32 m0, s49
	s_nop 0
	global_load_lds_dwordx4 v[154:155], off
	v_lshl_add_u64 v[154:155], v[152:153], 0, s[16:17]
	s_mov_b32 m0, s50
	s_nop 0
	global_load_lds_dwordx4 v[154:155], off
	v_lshl_add_u64 v[154:155], v[150:151], 0, s[20:21]
	s_mov_b32 m0, s51
	s_nop 0
	global_load_lds_dwordx4 v[154:155], off
	v_lshl_add_u64 v[154:155], v[152:153], 0, s[20:21]
	s_mov_b32 m0, s52
	s_nop 0
	global_load_lds_dwordx4 v[154:155], off
	s_branch .LBB0_1173
